# chunk transition matrices stored transposed by pass 1; combine phases hand-written: padded LDS rows, 16 conflict-free ds_read_b128 per step instead of 64 ds_read_b32
# speedup vs baseline: 1.0587x; 1.0195x over previous
;     static __device__ __forceinline__ void updP(float (&P)[64], const In1& in, float sa) {
;         float u0, u1, u2, u3;
;         asm volatile("v_mul_f32_dpp %0, %8, %4 row_newbcast:%17" DPPM "v_mul_f32_dpp %1, %9, %5 row_newbcast:%17" DPPM "v_mul_f32_dpp %2, %10, %6 row_newbcast:%17" DPPM "v_mul_f32_dpp %3, %11, %7 row_newbcast:%17" DPPM
;                      "v_fmac_f32_dpp %0, %12, %16 row_newbcast:%17" DPPM "v_fmac_f32_dpp %1, %13, %16 row_newbcast:%17" DPPM "v_fmac_f32_dpp %2, %14, %16 row_newbcast:%17" DPPM "v_fmac_f32_dpp %3, %15, %16 row_newbcast:%17" DPPM
;                      : "=&v"(u0), "=&v"(u1), "=&v"(u2), "=&v"(u3)
;                      : "v"(P[K]), "v"(P[K + 1]), "v"(P[K + 2]), "v"(P[K + 3]), "v"(in.w[0]), "v"(in.w[1]), "v"(in.w[2]), "v"(in.w[3]), "v"(in.b[0]), "v"(in.b[1]), "v"(in.b[2]), "v"(in.b[3]), "v"(sa), "n"(N0));
;         P[K] = u0; P[K + 1] = u1; P[K + 2] = u2; P[K + 3] = u3;
;         if constexpr (K + 4 < 64) ScanK<K + 4>::updP(P, in, sa);
.Lmy_p1d0_ldone_p:
	v_mul_f32_dpp v0, v216, v0 row_newbcast:0 row_mask:0xf bank_mask:0xf
	v_mul_f32_dpp v1, v217, v1 row_newbcast:0 row_mask:0xf bank_mask:0xf
	v_mul_f32_dpp v2, v218, v2 row_newbcast:0 row_mask:0xf bank_mask:0xf
	v_mul_f32_dpp v3, v219, v3 row_newbcast:0 row_mask:0xf bank_mask:0xf
	v_mul_f32_dpp v4, v216, v4 row_newbcast:1 row_mask:0xf bank_mask:0xf
	v_mul_f32_dpp v5, v217, v5 row_newbcast:1 row_mask:0xf bank_mask:0xf
	v_mul_f32_dpp v6, v218, v6 row_newbcast:1 row_mask:0xf bank_mask:0xf
	v_mul_f32_dpp v7, v219, v7 row_newbcast:1 row_mask:0xf bank_mask:0xf
	v_mul_f32_dpp v8, v216, v8 row_newbcast:2 row_mask:0xf bank_mask:0xf
	v_mul_f32_dpp v9, v217, v9 row_newbcast:2 row_mask:0xf bank_mask:0xf
	v_mul_f32_dpp v10, v218, v10 row_newbcast:2 row_mask:0xf bank_mask:0xf
	v_mul_f32_dpp v11, v219, v11 row_newbcast:2 row_mask:0xf bank_mask:0xf
	v_mul_f32_dpp v12, v216, v12 row_newbcast:3 row_mask:0xf bank_mask:0xf
	v_mul_f32_dpp v13, v217, v13 row_newbcast:3 row_mask:0xf bank_mask:0xf
	v_mul_f32_dpp v14, v218, v14 row_newbcast:3 row_mask:0xf bank_mask:0xf
	v_mul_f32_dpp v15, v219, v15 row_newbcast:3 row_mask:0xf bank_mask:0xf
	v_mul_f32_dpp v16, v216, v16 row_newbcast:4 row_mask:0xf bank_mask:0xf
	v_mul_f32_dpp v17, v217, v17 row_newbcast:4 row_mask:0xf bank_mask:0xf
	v_mul_f32_dpp v18, v218, v18 row_newbcast:4 row_mask:0xf bank_mask:0xf
	v_mul_f32_dpp v19, v219, v19 row_newbcast:4 row_mask:0xf bank_mask:0xf
	v_mul_f32_dpp v20, v216, v20 row_newbcast:5 row_mask:0xf bank_mask:0xf
	v_mul_f32_dpp v21, v217, v21 row_newbcast:5 row_mask:0xf bank_mask:0xf
	v_mul_f32_dpp v22, v218, v22 row_newbcast:5 row_mask:0xf bank_mask:0xf
	v_mul_f32_dpp v23, v219, v23 row_newbcast:5 row_mask:0xf bank_mask:0xf
	v_mul_f32_dpp v24, v216, v24 row_newbcast:6 row_mask:0xf bank_mask:0xf
	v_mul_f32_dpp v25, v217, v25 row_newbcast:6 row_mask:0xf bank_mask:0xf
	v_mul_f32_dpp v26, v218, v26 row_newbcast:6 row_mask:0xf bank_mask:0xf
	v_mul_f32_dpp v27, v219, v27 row_newbcast:6 row_mask:0xf bank_mask:0xf
	v_mul_f32_dpp v28, v216, v28 row_newbcast:7 row_mask:0xf bank_mask:0xf
	v_mul_f32_dpp v29, v217, v29 row_newbcast:7 row_mask:0xf bank_mask:0xf
	v_mul_f32_dpp v30, v218, v30 row_newbcast:7 row_mask:0xf bank_mask:0xf
	v_mul_f32_dpp v31, v219, v31 row_newbcast:7 row_mask:0xf bank_mask:0xf
	v_mul_f32_dpp v32, v216, v32 row_newbcast:8 row_mask:0xf bank_mask:0xf
	v_mul_f32_dpp v33, v217, v33 row_newbcast:8 row_mask:0xf bank_mask:0xf
	v_mul_f32_dpp v34, v218, v34 row_newbcast:8 row_mask:0xf bank_mask:0xf
	v_mul_f32_dpp v35, v219, v35 row_newbcast:8 row_mask:0xf bank_mask:0xf
	v_mul_f32_dpp v36, v216, v36 row_newbcast:9 row_mask:0xf bank_mask:0xf
	v_mul_f32_dpp v37, v217, v37 row_newbcast:9 row_mask:0xf bank_mask:0xf
	v_mul_f32_dpp v38, v218, v38 row_newbcast:9 row_mask:0xf bank_mask:0xf
	v_mul_f32_dpp v39, v219, v39 row_newbcast:9 row_mask:0xf bank_mask:0xf
	v_mul_f32_dpp v40, v216, v40 row_newbcast:10 row_mask:0xf bank_mask:0xf
	v_mul_f32_dpp v41, v217, v41 row_newbcast:10 row_mask:0xf bank_mask:0xf
	v_mul_f32_dpp v42, v218, v42 row_newbcast:10 row_mask:0xf bank_mask:0xf
	v_mul_f32_dpp v43, v219, v43 row_newbcast:10 row_mask:0xf bank_mask:0xf
	v_mul_f32_dpp v44, v216, v44 row_newbcast:11 row_mask:0xf bank_mask:0xf
	v_mul_f32_dpp v45, v217, v45 row_newbcast:11 row_mask:0xf bank_mask:0xf
	v_mul_f32_dpp v46, v218, v46 row_newbcast:11 row_mask:0xf bank_mask:0xf
	v_mul_f32_dpp v47, v219, v47 row_newbcast:11 row_mask:0xf bank_mask:0xf
	v_mul_f32_dpp v48, v216, v48 row_newbcast:12 row_mask:0xf bank_mask:0xf
	v_mul_f32_dpp v49, v217, v49 row_newbcast:12 row_mask:0xf bank_mask:0xf
	v_mul_f32_dpp v50, v218, v50 row_newbcast:12 row_mask:0xf bank_mask:0xf
	v_mul_f32_dpp v51, v219, v51 row_newbcast:12 row_mask:0xf bank_mask:0xf
	v_mul_f32_dpp v52, v216, v52 row_newbcast:13 row_mask:0xf bank_mask:0xf
	v_mul_f32_dpp v53, v217, v53 row_newbcast:13 row_mask:0xf bank_mask:0xf
	v_mul_f32_dpp v54, v218, v54 row_newbcast:13 row_mask:0xf bank_mask:0xf
	v_mul_f32_dpp v55, v219, v55 row_newbcast:13 row_mask:0xf bank_mask:0xf
	v_mul_f32_dpp v56, v216, v56 row_newbcast:14 row_mask:0xf bank_mask:0xf
; template <bool MIX> __device__ __forceinline__ void scan_pass1(const Params& p, int d, float* ldsf) {
;     ...
;         float* po = (isP ? PT : SLT) + ((size_t)(bh * NC + c)) * 4096 + lane * 64;
; #pragma unroll
;         for (int i = 0; i < 16; ++i) *(f32x4*)(po + 4 * i) = (f32x4){S[4 * i], S[4 * i + 1], S[4 * i + 2], S[4 * i + 3]};
	v_mul_f32_dpp v57, v217, v57 row_newbcast:14 row_mask:0xf bank_mask:0xf
	v_mul_f32_dpp v58, v218, v58 row_newbcast:14 row_mask:0xf bank_mask:0xf
	v_mul_f32_dpp v59, v219, v59 row_newbcast:14 row_mask:0xf bank_mask:0xf
	v_mul_f32_dpp v60, v216, v60 row_newbcast:15 row_mask:0xf bank_mask:0xf
	v_mul_f32_dpp v61, v217, v61 row_newbcast:15 row_mask:0xf bank_mask:0xf
	v_mul_f32_dpp v62, v218, v62 row_newbcast:15 row_mask:0xf bank_mask:0xf
	v_mul_f32_dpp v63, v219, v63 row_newbcast:15 row_mask:0xf bank_mask:0xf
	v_mov_b32_e32 v216, 1.0
	v_mov_b32_e32 v217, 1.0
	v_mov_b32_e32 v218, 1.0
	v_mov_b32_e32 v219, 1.0
	s_nop 1
	global_store_dword v207, v0, s[90:91] offset:0
	global_store_dword v207, v1, s[90:91] offset:256
	global_store_dword v207, v2, s[90:91] offset:512
	global_store_dword v207, v3, s[90:91] offset:768
	global_store_dword v207, v4, s[90:91] offset:1024
	global_store_dword v207, v5, s[90:91] offset:1280
	global_store_dword v207, v6, s[90:91] offset:1536
	global_store_dword v207, v7, s[90:91] offset:1792
	global_store_dword v207, v8, s[90:91] offset:2048
	global_store_dword v207, v9, s[90:91] offset:2304
	global_store_dword v207, v10, s[90:91] offset:2560
	global_store_dword v207, v11, s[90:91] offset:2816
	global_store_dword v207, v12, s[90:91] offset:3072
	global_store_dword v207, v13, s[90:91] offset:3328
	global_store_dword v207, v14, s[90:91] offset:3584
	global_store_dword v207, v15, s[90:91] offset:3840
	s_add_u32 s90, s90, 0x1000
	s_addc_u32 s91, s91, 0
	global_store_dword v207, v16, s[90:91] offset:0
	global_store_dword v207, v17, s[90:91] offset:256
	global_store_dword v207, v18, s[90:91] offset:512
	global_store_dword v207, v19, s[90:91] offset:768
	global_store_dword v207, v20, s[90:91] offset:1024
	global_store_dword v207, v21, s[90:91] offset:1280
	global_store_dword v207, v22, s[90:91] offset:1536
	global_store_dword v207, v23, s[90:91] offset:1792
	global_store_dword v207, v24, s[90:91] offset:2048
	global_store_dword v207, v25, s[90:91] offset:2304
	global_store_dword v207, v26, s[90:91] offset:2560
	global_store_dword v207, v27, s[90:91] offset:2816
	global_store_dword v207, v28, s[90:91] offset:3072
	global_store_dword v207, v29, s[90:91] offset:3328
	global_store_dword v207, v30, s[90:91] offset:3584
	global_store_dword v207, v31, s[90:91] offset:3840
	s_add_u32 s90, s90, 0x1000
	s_addc_u32 s91, s91, 0
	global_store_dword v207, v32, s[90:91] offset:0
	global_store_dword v207, v33, s[90:91] offset:256
	global_store_dword v207, v34, s[90:91] offset:512
	global_store_dword v207, v35, s[90:91] offset:768
	global_store_dword v207, v36, s[90:91] offset:1024
	global_store_dword v207, v37, s[90:91] offset:1280
	global_store_dword v207, v38, s[90:91] offset:1536
	global_store_dword v207, v39, s[90:91] offset:1792
	global_store_dword v207, v40, s[90:91] offset:2048
	global_store_dword v207, v41, s[90:91] offset:2304
	global_store_dword v207, v42, s[90:91] offset:2560
	global_store_dword v207, v43, s[90:91] offset:2816
	global_store_dword v207, v44, s[90:91] offset:3072
	global_store_dword v207, v45, s[90:91] offset:3328
	global_store_dword v207, v46, s[90:91] offset:3584
	global_store_dword v207, v47, s[90:91] offset:3840
	s_add_u32 s90, s90, 0x1000
	s_addc_u32 s91, s91, 0
	global_store_dword v207, v48, s[90:91] offset:0
	global_store_dword v207, v49, s[90:91] offset:256
	global_store_dword v207, v50, s[90:91] offset:512
	global_store_dword v207, v51, s[90:91] offset:768
	global_store_dword v207, v52, s[90:91] offset:1024
	global_store_dword v207, v53, s[90:91] offset:1280
	global_store_dword v207, v54, s[90:91] offset:1536
	global_store_dword v207, v55, s[90:91] offset:1792
	global_store_dword v207, v56, s[90:91] offset:2048
	global_store_dword v207, v57, s[90:91] offset:2304
	global_store_dword v207, v58, s[90:91] offset:2560
	global_store_dword v207, v59, s[90:91] offset:2816
	global_store_dword v207, v60, s[90:91] offset:3072
	global_store_dword v207, v61, s[90:91] offset:3328
	global_store_dword v207, v62, s[90:91] offset:3584
	global_store_dword v207, v63, s[90:91] offset:3840
	s_branch .Lmy_p1d0_stored

; #define NEXT_ITEM() (MIX ? (int)__builtin_amdgcn_readfirstlane(lane == 0 ? __hip_atomic_fetch_add(qctr, 1u, __ATOMIC_RELAXED, __HIP_MEMORY_SCOPE_AGENT) : 0u) : item + (int)gridDim.x * 8)
; template <bool MIX> __device__ __forceinline__ void scan_pass1(const Params& p, int d, float* ldsf) {
;     ...
;     for (int item = MIX ? NEXT_ITEM() : (int)(blockIdx.x * 8 + wid); item < 2 * NS; item = NEXT_ITEM()) {
.Lmy_p1d0_stored:
	s_nop 1
	v_mov_b32_e32 v214, 0
	v_mov_b32_e32 v215, 1
	s_mov_b64 exec, 1
	global_atomic_add v214, v214, v215, s[34:35] sc0
	s_mov_b64 exec, -1
	s_waitcnt vmcnt(0)
	s_nop 0
	v_readfirstlane_b32 s0, v214
	s_nop 3
	s_branch .Lmy_p1d0_item

; #define LAS __attribute__((address_space(3)))
; __device__ __forceinline__ void scan_combine(const Params& p, unsigned char* lds) {
;     const int tid = threadIdx.x, lane = tid & 63, wid = __builtin_amdgcn_readfirstlane(tid >> 6), l15 = lane & 15;
;     const float* PT = (const float*)(p.ws + O_PT); const float* SLT = (const float*)(p.ws + O_SLT); float* SIT = (float*)(p.ws + O_SIT);
;     LAS float* pbuf = (LAS float*)(LAS unsigned char*)lds;
;     LAS float* rowb = pbuf + 8192 + wid * 64;
;     for (int item = blockIdx.x; item < 256; item += gridDim.x) {
;         const int bh = item >> 3, row = (item & 7) * 8 + wid;
;         const float* pt = PT + (size_t)bh * NC * 4096 + tid * 8; const float* st = SLT + (size_t)bh * NC * 4096 + row * 64 + lane; float* si = SIT + (size_t)bh * NC * 4096 + row * 64 + lane;
;         __syncthreads();
;         { const f32x4 pa = *(const f32x4*)pt, pb = *(const f32x4*)(pt + 4); *(LAS f32x4*)(pbuf + tid * 8) = pa; *(LAS f32x4*)(pbuf + tid * 8 + 4) = pb; }
;     ...
;         f32x4 pa0, pb0, pa1, pb1, pa2, pb2; float sl0, sl1, sl2;
;         PLD(pa0, pb0, 1); PLD(pa1, pb1, 2); PLD(pa2, pb2, 3); SLD(sl0, 0); SLD(sl1, 1); SLD(sl2, 2);
;         float sq[4] = {0.f, 0.f, 0.f, 0.f};
;         __syncthreads();
.LBB0_628:
	s_cmp_lt_i32 s58, 6
	s_cselect_b64 s[0:1], -1, 0
	s_cmp_gt_i32 s59, 5
	s_cselect_b64 s[4:5], -1, 0
	s_and_b64 s[0:1], s[0:1], s[4:5]
	s_andn2_b64 vcc, exec, s[0:1]
	s_cbranch_vccnz .LBB0_688
	v_readfirstlane_b32 s0, v254
	s_nop 3
	s_lshr_b32 s1, s0, 6
	v_and_b32_e32 v114, 63, v254
	v_lshlrev_b32_e32 v108, 2, v114
	v_mul_u32_u24_e32 v116, 272, v114
	v_lshlrev_b32_e32 v112, 5, v254
	v_lshrrev_b32_e32 v109, 3, v254
	v_mul_u32_u24_e32 v109, 272, v109
	v_and_b32_e32 v115, 7, v254
	v_lshl_add_u32 v109, v115, 5, v109
	s_lshl_b32 s4, s1, 8
	s_add_u32 s4, s4, 0x9000
	v_add_u32_e32 v110, s4, v108
	v_and_b32_e32 v115, 15, v254
	v_lshlrev_b32_e32 v115, 2, v115
	v_add_u32_e32 v111, s4, v115
	s_mov_b32 s0, s2
.Lmy_cmb0_item:
	s_cmpk_gt_i32 s0, 0xff
	s_cbranch_scc1 .Lmy_cmb0_end
	s_lshr_b32 s4, s0, 3
	s_lshl_b32 s4, s4, 20
	s_and_b32 s5, s0, 7
	s_lshl_b32 s5, s5, 3
	s_add_u32 s5, s5, s1
	v_mov_b32_e32 v114, s5
	v_lshlrev_b32_e32 v114, 8, v114
	v_add_u32_e32 v113, v114, v108
	s_add_u32 s6, s4, 0x13800000
	s_add_u32 s64, s56, s6
	s_addc_u32 s65, s57, 0
	s_add_u32 s6, s4, 0x15800000
	s_add_u32 s66, s56, s6
	s_addc_u32 s67, s57, 0
	s_add_u32 s6, s4, 0x3da00000
	s_add_u32 s68, s56, s6
	s_addc_u32 s69, s57, 0
	s_waitcnt vmcnt(0) lgkmcnt(0)
	s_barrier
	global_load_dwordx4 v[0:3], v112, s[64:65]
	global_load_dwordx4 v[4:7], v112, s[64:65] offset:16
	s_add_u32 s6, s64, 0x4000
	s_addc_u32 s7, s65, 0
	global_load_dwordx4 v[64:67], v112, s[6:7]
	global_load_dwordx4 v[68:71], v112, s[6:7] offset:16
	s_add_u32 s6, s66, 0x0
	s_addc_u32 s7, s67, 0
	global_load_dword v72, v113, s[6:7]
	s_add_u32 s6, s64, 0x8000
	s_addc_u32 s7, s65, 0
	global_load_dwordx4 v[76:79], v112, s[6:7]
	global_load_dwordx4 v[80:83], v112, s[6:7] offset:16
	s_add_u32 s6, s66, 0x4000
	s_addc_u32 s7, s67, 0
	global_load_dword v84, v113, s[6:7]
	s_add_u32 s6, s64, 0xc000
	s_addc_u32 s7, s65, 0
	global_load_dwordx4 v[88:91], v112, s[6:7]
	global_load_dwordx4 v[92:95], v112, s[6:7] offset:16
	s_add_u32 s6, s66, 0x8000
	s_addc_u32 s7, s67, 0
	global_load_dword v96, v113, s[6:7]
	s_mov_b32 s70, 0x10000
	s_mov_b32 s71, 0xc000
	s_mov_b32 s73, 0x4000
	s_mov_b32 s74, 0
	v_mov_b32_e32 v100, 0
	v_mov_b32_e32 v101, 0
	v_mov_b32_e32 v102, 0
	v_mov_b32_e32 v103, 0
	s_waitcnt vmcnt(9)
	ds_write_b128 v109, v[0:3]
	ds_write_b128 v109, v[4:7] offset:16
	s_waitcnt vmcnt(0) lgkmcnt(0)
	s_barrier
	s_movk_i32 s72, 21
.Lmy_cmb0_loop:
	v_add_u32_e32 v114, s74, v116
	ds_read_b128 v[0:3], v114 offset:0
	ds_read_b128 v[4:7], v114 offset:16
	ds_read_b128 v[8:11], v114 offset:32
	ds_read_b128 v[12:15], v114 offset:48
	ds_read_b128 v[16:19], v114 offset:64
	ds_read_b128 v[20:23], v114 offset:80
	ds_read_b128 v[24:27], v114 offset:96
	ds_read_b128 v[28:31], v114 offset:112
	ds_read_b128 v[32:35], v114 offset:128
	ds_read_b128 v[36:39], v114 offset:144
	ds_read_b128 v[40:43], v114 offset:160
	ds_read_b128 v[44:47], v114 offset:176
	ds_read_b128 v[48:51], v114 offset:192
	ds_read_b128 v[52:55], v114 offset:208
	ds_read_b128 v[56:59], v114 offset:224
	ds_read_b128 v[60:63], v114 offset:240
	s_waitcnt vmcnt(8)
	v_mov_b32_e32 v104, v72
	v_mov_b32_e32 v105, 0
	v_mov_b32_e32 v106, 0
	v_mov_b32_e32 v107, 0
	s_waitcnt lgkmcnt(0)
	v_fmac_f32_dpp v104, v100, v0 row_newbcast:0 row_mask:0xf bank_mask:0xf
	v_fmac_f32_dpp v105, v101, v16 row_newbcast:0 row_mask:0xf bank_mask:0xf
	v_fmac_f32_dpp v106, v102, v32 row_newbcast:0 row_mask:0xf bank_mask:0xf
	v_fmac_f32_dpp v107, v103, v48 row_newbcast:0 row_mask:0xf bank_mask:0xf
	v_fmac_f32_dpp v104, v100, v1 row_newbcast:1 row_mask:0xf bank_mask:0xf
	v_fmac_f32_dpp v105, v101, v17 row_newbcast:1 row_mask:0xf bank_mask:0xf
	v_fmac_f32_dpp v106, v102, v33 row_newbcast:1 row_mask:0xf bank_mask:0xf
	v_fmac_f32_dpp v107, v103, v49 row_newbcast:1 row_mask:0xf bank_mask:0xf
	v_fmac_f32_dpp v104, v100, v2 row_newbcast:2 row_mask:0xf bank_mask:0xf
	v_fmac_f32_dpp v105, v101, v18 row_newbcast:2 row_mask:0xf bank_mask:0xf
	v_fmac_f32_dpp v106, v102, v34 row_newbcast:2 row_mask:0xf bank_mask:0xf
	v_fmac_f32_dpp v107, v103, v50 row_newbcast:2 row_mask:0xf bank_mask:0xf
	v_fmac_f32_dpp v104, v100, v3 row_newbcast:3 row_mask:0xf bank_mask:0xf
	v_fmac_f32_dpp v105, v101, v19 row_newbcast:3 row_mask:0xf bank_mask:0xf
	v_fmac_f32_dpp v106, v102, v35 row_newbcast:3 row_mask:0xf bank_mask:0xf
	v_fmac_f32_dpp v107, v103, v51 row_newbcast:3 row_mask:0xf bank_mask:0xf
	v_fmac_f32_dpp v104, v100, v4 row_newbcast:4 row_mask:0xf bank_mask:0xf
	v_fmac_f32_dpp v105, v101, v20 row_newbcast:4 row_mask:0xf bank_mask:0xf
	v_fmac_f32_dpp v106, v102, v36 row_newbcast:4 row_mask:0xf bank_mask:0xf
	v_fmac_f32_dpp v107, v103, v52 row_newbcast:4 row_mask:0xf bank_mask:0xf
	v_fmac_f32_dpp v104, v100, v5 row_newbcast:5 row_mask:0xf bank_mask:0xf
	v_fmac_f32_dpp v105, v101, v21 row_newbcast:5 row_mask:0xf bank_mask:0xf
	v_fmac_f32_dpp v106, v102, v37 row_newbcast:5 row_mask:0xf bank_mask:0xf
	v_fmac_f32_dpp v107, v103, v53 row_newbcast:5 row_mask:0xf bank_mask:0xf
	v_fmac_f32_dpp v104, v100, v6 row_newbcast:6 row_mask:0xf bank_mask:0xf
	v_fmac_f32_dpp v105, v101, v22 row_newbcast:6 row_mask:0xf bank_mask:0xf
	v_fmac_f32_dpp v106, v102, v38 row_newbcast:6 row_mask:0xf bank_mask:0xf
	v_fmac_f32_dpp v107, v103, v54 row_newbcast:6 row_mask:0xf bank_mask:0xf
	v_fmac_f32_dpp v104, v100, v7 row_newbcast:7 row_mask:0xf bank_mask:0xf
	v_fmac_f32_dpp v105, v101, v23 row_newbcast:7 row_mask:0xf bank_mask:0xf
	v_fmac_f32_dpp v106, v102, v39 row_newbcast:7 row_mask:0xf bank_mask:0xf
	v_fmac_f32_dpp v107, v103, v55 row_newbcast:7 row_mask:0xf bank_mask:0xf
	v_fmac_f32_dpp v104, v100, v8 row_newbcast:8 row_mask:0xf bank_mask:0xf
	v_fmac_f32_dpp v105, v101, v24 row_newbcast:8 row_mask:0xf bank_mask:0xf
	v_fmac_f32_dpp v106, v102, v40 row_newbcast:8 row_mask:0xf bank_mask:0xf
	v_fmac_f32_dpp v107, v103, v56 row_newbcast:8 row_mask:0xf bank_mask:0xf
	v_fmac_f32_dpp v104, v100, v9 row_newbcast:9 row_mask:0xf bank_mask:0xf
	v_fmac_f32_dpp v105, v101, v25 row_newbcast:9 row_mask:0xf bank_mask:0xf
	v_fmac_f32_dpp v106, v102, v41 row_newbcast:9 row_mask:0xf bank_mask:0xf
	v_fmac_f32_dpp v107, v103, v57 row_newbcast:9 row_mask:0xf bank_mask:0xf
	v_fmac_f32_dpp v104, v100, v10 row_newbcast:10 row_mask:0xf bank_mask:0xf
	v_fmac_f32_dpp v105, v101, v26 row_newbcast:10 row_mask:0xf bank_mask:0xf
	v_fmac_f32_dpp v106, v102, v42 row_newbcast:10 row_mask:0xf bank_mask:0xf
	v_fmac_f32_dpp v107, v103, v58 row_newbcast:10 row_mask:0xf bank_mask:0xf
	v_fmac_f32_dpp v104, v100, v11 row_newbcast:11 row_mask:0xf bank_mask:0xf
	v_fmac_f32_dpp v105, v101, v27 row_newbcast:11 row_mask:0xf bank_mask:0xf
	v_fmac_f32_dpp v106, v102, v43 row_newbcast:11 row_mask:0xf bank_mask:0xf
	v_fmac_f32_dpp v107, v103, v59 row_newbcast:11 row_mask:0xf bank_mask:0xf
	v_fmac_f32_dpp v104, v100, v12 row_newbcast:12 row_mask:0xf bank_mask:0xf
	v_fmac_f32_dpp v105, v101, v28 row_newbcast:12 row_mask:0xf bank_mask:0xf
	v_fmac_f32_dpp v106, v102, v44 row_newbcast:12 row_mask:0xf bank_mask:0xf
	v_fmac_f32_dpp v107, v103, v60 row_newbcast:12 row_mask:0xf bank_mask:0xf
	v_fmac_f32_dpp v104, v100, v13 row_newbcast:13 row_mask:0xf bank_mask:0xf
	v_fmac_f32_dpp v105, v101, v29 row_newbcast:13 row_mask:0xf bank_mask:0xf
	v_fmac_f32_dpp v106, v102, v45 row_newbcast:13 row_mask:0xf bank_mask:0xf
	v_fmac_f32_dpp v107, v103, v61 row_newbcast:13 row_mask:0xf bank_mask:0xf
	v_fmac_f32_dpp v104, v100, v14 row_newbcast:14 row_mask:0xf bank_mask:0xf
	v_fmac_f32_dpp v105, v101, v30 row_newbcast:14 row_mask:0xf bank_mask:0xf
	v_fmac_f32_dpp v106, v102, v46 row_newbcast:14 row_mask:0xf bank_mask:0xf
	v_fmac_f32_dpp v107, v103, v62 row_newbcast:14 row_mask:0xf bank_mask:0xf
	v_fmac_f32_dpp v104, v100, v15 row_newbcast:15 row_mask:0xf bank_mask:0xf
	v_fmac_f32_dpp v105, v101, v31 row_newbcast:15 row_mask:0xf bank_mask:0xf
	v_fmac_f32_dpp v106, v102, v47 row_newbcast:15 row_mask:0xf bank_mask:0xf
	v_fmac_f32_dpp v107, v103, v63 row_newbcast:15 row_mask:0xf bank_mask:0xf
	v_add_f32_e32 v104, v104, v105
	v_add_f32_e32 v106, v106, v107
	v_add_f32_e32 v104, v104, v106
	ds_write_b32 v110, v104
	s_add_u32 s6, s68, s73
	s_addc_u32 s7, s69, 0
	global_store_dword v113, v104, s[6:7]
	s_add_u32 s73, s73, 0x4000
	ds_read_b32 v100, v111 offset:0
	ds_read_b32 v101, v111 offset:64
	ds_read_b32 v102, v111 offset:128
	ds_read_b32 v103, v111 offset:192
	s_xor_b32 s74, s74, 0x4400
	v_add_u32_e32 v114, s74, v109
	ds_write_b128 v114, v[64:67]
	ds_write_b128 v114, v[68:71] offset:16
	s_min_u32 s4, s70, 0xf8000
	s_add_u32 s6, s64, s4
	s_addc_u32 s7, s65, 0
	s_nop 0
	global_load_dwordx4 v[64:67], v112, s[6:7]
	global_load_dwordx4 v[68:71], v112, s[6:7] offset:16
	s_min_u32 s4, s71, 0xf8000
	s_add_u32 s6, s66, s4
	s_addc_u32 s7, s67, 0
	global_load_dword v72, v113, s[6:7]
	s_add_u32 s70, s70, 0x4000
	s_add_u32 s71, s71, 0x4000
	s_waitcnt lgkmcnt(0)
	s_barrier
	v_add_u32_e32 v114, s74, v116
	ds_read_b128 v[0:3], v114 offset:0
	ds_read_b128 v[4:7], v114 offset:16
	ds_read_b128 v[8:11], v114 offset:32
	ds_read_b128 v[12:15], v114 offset:48
	ds_read_b128 v[16:19], v114 offset:64
	ds_read_b128 v[20:23], v114 offset:80
	ds_read_b128 v[24:27], v114 offset:96
	ds_read_b128 v[28:31], v114 offset:112
	ds_read_b128 v[32:35], v114 offset:128
	ds_read_b128 v[36:39], v114 offset:144
	ds_read_b128 v[40:43], v114 offset:160
	ds_read_b128 v[44:47], v114 offset:176
	ds_read_b128 v[48:51], v114 offset:192
	ds_read_b128 v[52:55], v114 offset:208
	ds_read_b128 v[56:59], v114 offset:224
	ds_read_b128 v[60:63], v114 offset:240
	s_waitcnt vmcnt(8)
	v_mov_b32_e32 v104, v84
	v_mov_b32_e32 v105, 0
	v_mov_b32_e32 v106, 0
	v_mov_b32_e32 v107, 0
	s_waitcnt lgkmcnt(0)
	v_fmac_f32_dpp v104, v100, v0 row_newbcast:0 row_mask:0xf bank_mask:0xf
	v_fmac_f32_dpp v105, v101, v16 row_newbcast:0 row_mask:0xf bank_mask:0xf
	v_fmac_f32_dpp v106, v102, v32 row_newbcast:0 row_mask:0xf bank_mask:0xf
	v_fmac_f32_dpp v107, v103, v48 row_newbcast:0 row_mask:0xf bank_mask:0xf
	v_fmac_f32_dpp v104, v100, v1 row_newbcast:1 row_mask:0xf bank_mask:0xf
	v_fmac_f32_dpp v105, v101, v17 row_newbcast:1 row_mask:0xf bank_mask:0xf
	v_fmac_f32_dpp v106, v102, v33 row_newbcast:1 row_mask:0xf bank_mask:0xf
	v_fmac_f32_dpp v107, v103, v49 row_newbcast:1 row_mask:0xf bank_mask:0xf
	v_fmac_f32_dpp v104, v100, v2 row_newbcast:2 row_mask:0xf bank_mask:0xf
	v_fmac_f32_dpp v105, v101, v18 row_newbcast:2 row_mask:0xf bank_mask:0xf
	v_fmac_f32_dpp v106, v102, v34 row_newbcast:2 row_mask:0xf bank_mask:0xf
	v_fmac_f32_dpp v107, v103, v50 row_newbcast:2 row_mask:0xf bank_mask:0xf
	v_fmac_f32_dpp v104, v100, v3 row_newbcast:3 row_mask:0xf bank_mask:0xf
	v_fmac_f32_dpp v105, v101, v19 row_newbcast:3 row_mask:0xf bank_mask:0xf
	v_fmac_f32_dpp v106, v102, v35 row_newbcast:3 row_mask:0xf bank_mask:0xf
	v_fmac_f32_dpp v107, v103, v51 row_newbcast:3 row_mask:0xf bank_mask:0xf
	v_fmac_f32_dpp v104, v100, v4 row_newbcast:4 row_mask:0xf bank_mask:0xf
	v_fmac_f32_dpp v105, v101, v20 row_newbcast:4 row_mask:0xf bank_mask:0xf
	v_fmac_f32_dpp v106, v102, v36 row_newbcast:4 row_mask:0xf bank_mask:0xf
	v_fmac_f32_dpp v107, v103, v52 row_newbcast:4 row_mask:0xf bank_mask:0xf
	v_fmac_f32_dpp v104, v100, v5 row_newbcast:5 row_mask:0xf bank_mask:0xf
	v_fmac_f32_dpp v105, v101, v21 row_newbcast:5 row_mask:0xf bank_mask:0xf
	v_fmac_f32_dpp v106, v102, v37 row_newbcast:5 row_mask:0xf bank_mask:0xf
	v_fmac_f32_dpp v107, v103, v53 row_newbcast:5 row_mask:0xf bank_mask:0xf
	v_fmac_f32_dpp v104, v100, v6 row_newbcast:6 row_mask:0xf bank_mask:0xf
	v_fmac_f32_dpp v105, v101, v22 row_newbcast:6 row_mask:0xf bank_mask:0xf
	v_fmac_f32_dpp v106, v102, v38 row_newbcast:6 row_mask:0xf bank_mask:0xf
	v_fmac_f32_dpp v107, v103, v54 row_newbcast:6 row_mask:0xf bank_mask:0xf
	v_fmac_f32_dpp v104, v100, v7 row_newbcast:7 row_mask:0xf bank_mask:0xf
	v_fmac_f32_dpp v105, v101, v23 row_newbcast:7 row_mask:0xf bank_mask:0xf
	v_fmac_f32_dpp v106, v102, v39 row_newbcast:7 row_mask:0xf bank_mask:0xf
	v_fmac_f32_dpp v107, v103, v55 row_newbcast:7 row_mask:0xf bank_mask:0xf
	v_fmac_f32_dpp v104, v100, v8 row_newbcast:8 row_mask:0xf bank_mask:0xf
	v_fmac_f32_dpp v105, v101, v24 row_newbcast:8 row_mask:0xf bank_mask:0xf
	v_fmac_f32_dpp v106, v102, v40 row_newbcast:8 row_mask:0xf bank_mask:0xf
	v_fmac_f32_dpp v107, v103, v56 row_newbcast:8 row_mask:0xf bank_mask:0xf
	v_fmac_f32_dpp v104, v100, v9 row_newbcast:9 row_mask:0xf bank_mask:0xf
	v_fmac_f32_dpp v105, v101, v25 row_newbcast:9 row_mask:0xf bank_mask:0xf
	v_fmac_f32_dpp v106, v102, v41 row_newbcast:9 row_mask:0xf bank_mask:0xf
	v_fmac_f32_dpp v107, v103, v57 row_newbcast:9 row_mask:0xf bank_mask:0xf
	v_fmac_f32_dpp v104, v100, v10 row_newbcast:10 row_mask:0xf bank_mask:0xf
	v_fmac_f32_dpp v105, v101, v26 row_newbcast:10 row_mask:0xf bank_mask:0xf
	v_fmac_f32_dpp v106, v102, v42 row_newbcast:10 row_mask:0xf bank_mask:0xf
	v_fmac_f32_dpp v107, v103, v58 row_newbcast:10 row_mask:0xf bank_mask:0xf
	v_fmac_f32_dpp v104, v100, v11 row_newbcast:11 row_mask:0xf bank_mask:0xf
	v_fmac_f32_dpp v105, v101, v27 row_newbcast:11 row_mask:0xf bank_mask:0xf
	v_fmac_f32_dpp v106, v102, v43 row_newbcast:11 row_mask:0xf bank_mask:0xf
	v_fmac_f32_dpp v107, v103, v59 row_newbcast:11 row_mask:0xf bank_mask:0xf
	v_fmac_f32_dpp v104, v100, v12 row_newbcast:12 row_mask:0xf bank_mask:0xf
	v_fmac_f32_dpp v105, v101, v28 row_newbcast:12 row_mask:0xf bank_mask:0xf
	v_fmac_f32_dpp v106, v102, v44 row_newbcast:12 row_mask:0xf bank_mask:0xf
	v_fmac_f32_dpp v107, v103, v60 row_newbcast:12 row_mask:0xf bank_mask:0xf
	v_fmac_f32_dpp v104, v100, v13 row_newbcast:13 row_mask:0xf bank_mask:0xf
	v_fmac_f32_dpp v105, v101, v29 row_newbcast:13 row_mask:0xf bank_mask:0xf
	v_fmac_f32_dpp v106, v102, v45 row_newbcast:13 row_mask:0xf bank_mask:0xf
	v_fmac_f32_dpp v107, v103, v61 row_newbcast:13 row_mask:0xf bank_mask:0xf
	v_fmac_f32_dpp v104, v100, v14 row_newbcast:14 row_mask:0xf bank_mask:0xf
	v_fmac_f32_dpp v105, v101, v30 row_newbcast:14 row_mask:0xf bank_mask:0xf
	v_fmac_f32_dpp v106, v102, v46 row_newbcast:14 row_mask:0xf bank_mask:0xf
	v_fmac_f32_dpp v107, v103, v62 row_newbcast:14 row_mask:0xf bank_mask:0xf
	v_fmac_f32_dpp v104, v100, v15 row_newbcast:15 row_mask:0xf bank_mask:0xf
	v_fmac_f32_dpp v105, v101, v31 row_newbcast:15 row_mask:0xf bank_mask:0xf
	v_fmac_f32_dpp v106, v102, v47 row_newbcast:15 row_mask:0xf bank_mask:0xf
	v_fmac_f32_dpp v107, v103, v63 row_newbcast:15 row_mask:0xf bank_mask:0xf
	v_add_f32_e32 v104, v104, v105
	v_add_f32_e32 v106, v106, v107
	v_add_f32_e32 v104, v104, v106
	ds_write_b32 v110, v104
	s_add_u32 s6, s68, s73
	s_addc_u32 s7, s69, 0
	global_store_dword v113, v104, s[6:7]
	s_add_u32 s73, s73, 0x4000
	ds_read_b32 v100, v111 offset:0
	ds_read_b32 v101, v111 offset:64
	ds_read_b32 v102, v111 offset:128
	ds_read_b32 v103, v111 offset:192
	s_xor_b32 s74, s74, 0x4400
	v_add_u32_e32 v114, s74, v109
	ds_write_b128 v114, v[76:79]
	ds_write_b128 v114, v[80:83] offset:16
	s_min_u32 s4, s70, 0xf8000
	s_add_u32 s6, s64, s4
	s_addc_u32 s7, s65, 0
	s_nop 0
	global_load_dwordx4 v[76:79], v112, s[6:7]
	global_load_dwordx4 v[80:83], v112, s[6:7] offset:16
	s_min_u32 s4, s71, 0xf8000
	s_add_u32 s6, s66, s4
	s_addc_u32 s7, s67, 0
	global_load_dword v84, v113, s[6:7]
	s_add_u32 s70, s70, 0x4000
	s_add_u32 s71, s71, 0x4000
	s_waitcnt lgkmcnt(0)
	s_barrier
; __device__ __forceinline__ void scan_combine(const Params& p, unsigned char* lds) {
;     ...
; #pragma unroll 1
;         for (int c = 0; c < NC - 1; c += 3) { CSTEP(c, pa0, pb0, sl0); CSTEP(c + 1, pa1, pb1, sl1); CSTEP(c + 2, pa2, pb2, sl2); }
	v_add_u32_e32 v114, s74, v116
	ds_read_b128 v[0:3], v114 offset:0
	ds_read_b128 v[4:7], v114 offset:16
	ds_read_b128 v[8:11], v114 offset:32
	ds_read_b128 v[12:15], v114 offset:48
	ds_read_b128 v[16:19], v114 offset:64
	ds_read_b128 v[20:23], v114 offset:80
	ds_read_b128 v[24:27], v114 offset:96
	ds_read_b128 v[28:31], v114 offset:112
	ds_read_b128 v[32:35], v114 offset:128
	ds_read_b128 v[36:39], v114 offset:144
	ds_read_b128 v[40:43], v114 offset:160
	ds_read_b128 v[44:47], v114 offset:176
	ds_read_b128 v[48:51], v114 offset:192
	ds_read_b128 v[52:55], v114 offset:208
	ds_read_b128 v[56:59], v114 offset:224
	ds_read_b128 v[60:63], v114 offset:240
	s_waitcnt vmcnt(8)
	v_mov_b32_e32 v104, v96
	v_mov_b32_e32 v105, 0
	v_mov_b32_e32 v106, 0
	v_mov_b32_e32 v107, 0
	s_waitcnt lgkmcnt(0)
	v_fmac_f32_dpp v104, v100, v0 row_newbcast:0 row_mask:0xf bank_mask:0xf
	v_fmac_f32_dpp v105, v101, v16 row_newbcast:0 row_mask:0xf bank_mask:0xf
	v_fmac_f32_dpp v106, v102, v32 row_newbcast:0 row_mask:0xf bank_mask:0xf
	v_fmac_f32_dpp v107, v103, v48 row_newbcast:0 row_mask:0xf bank_mask:0xf
	v_fmac_f32_dpp v104, v100, v1 row_newbcast:1 row_mask:0xf bank_mask:0xf
	v_fmac_f32_dpp v105, v101, v17 row_newbcast:1 row_mask:0xf bank_mask:0xf
	v_fmac_f32_dpp v106, v102, v33 row_newbcast:1 row_mask:0xf bank_mask:0xf
	v_fmac_f32_dpp v107, v103, v49 row_newbcast:1 row_mask:0xf bank_mask:0xf
	v_fmac_f32_dpp v104, v100, v2 row_newbcast:2 row_mask:0xf bank_mask:0xf
	v_fmac_f32_dpp v105, v101, v18 row_newbcast:2 row_mask:0xf bank_mask:0xf
	v_fmac_f32_dpp v106, v102, v34 row_newbcast:2 row_mask:0xf bank_mask:0xf
	v_fmac_f32_dpp v107, v103, v50 row_newbcast:2 row_mask:0xf bank_mask:0xf
	v_fmac_f32_dpp v104, v100, v3 row_newbcast:3 row_mask:0xf bank_mask:0xf
	v_fmac_f32_dpp v105, v101, v19 row_newbcast:3 row_mask:0xf bank_mask:0xf
	v_fmac_f32_dpp v106, v102, v35 row_newbcast:3 row_mask:0xf bank_mask:0xf
	v_fmac_f32_dpp v107, v103, v51 row_newbcast:3 row_mask:0xf bank_mask:0xf
	v_fmac_f32_dpp v104, v100, v4 row_newbcast:4 row_mask:0xf bank_mask:0xf
	v_fmac_f32_dpp v105, v101, v20 row_newbcast:4 row_mask:0xf bank_mask:0xf
	v_fmac_f32_dpp v106, v102, v36 row_newbcast:4 row_mask:0xf bank_mask:0xf
	v_fmac_f32_dpp v107, v103, v52 row_newbcast:4 row_mask:0xf bank_mask:0xf
	v_fmac_f32_dpp v104, v100, v5 row_newbcast:5 row_mask:0xf bank_mask:0xf
	v_fmac_f32_dpp v105, v101, v21 row_newbcast:5 row_mask:0xf bank_mask:0xf
	v_fmac_f32_dpp v106, v102, v37 row_newbcast:5 row_mask:0xf bank_mask:0xf
	v_fmac_f32_dpp v107, v103, v53 row_newbcast:5 row_mask:0xf bank_mask:0xf
	v_fmac_f32_dpp v104, v100, v6 row_newbcast:6 row_mask:0xf bank_mask:0xf
	v_fmac_f32_dpp v105, v101, v22 row_newbcast:6 row_mask:0xf bank_mask:0xf
	v_fmac_f32_dpp v106, v102, v38 row_newbcast:6 row_mask:0xf bank_mask:0xf
	v_fmac_f32_dpp v107, v103, v54 row_newbcast:6 row_mask:0xf bank_mask:0xf
	v_fmac_f32_dpp v104, v100, v7 row_newbcast:7 row_mask:0xf bank_mask:0xf
	v_fmac_f32_dpp v105, v101, v23 row_newbcast:7 row_mask:0xf bank_mask:0xf
	v_fmac_f32_dpp v106, v102, v39 row_newbcast:7 row_mask:0xf bank_mask:0xf
	v_fmac_f32_dpp v107, v103, v55 row_newbcast:7 row_mask:0xf bank_mask:0xf
	v_fmac_f32_dpp v104, v100, v8 row_newbcast:8 row_mask:0xf bank_mask:0xf
	v_fmac_f32_dpp v105, v101, v24 row_newbcast:8 row_mask:0xf bank_mask:0xf
	v_fmac_f32_dpp v106, v102, v40 row_newbcast:8 row_mask:0xf bank_mask:0xf
	v_fmac_f32_dpp v107, v103, v56 row_newbcast:8 row_mask:0xf bank_mask:0xf
	v_fmac_f32_dpp v104, v100, v9 row_newbcast:9 row_mask:0xf bank_mask:0xf
	v_fmac_f32_dpp v105, v101, v25 row_newbcast:9 row_mask:0xf bank_mask:0xf
	v_fmac_f32_dpp v106, v102, v41 row_newbcast:9 row_mask:0xf bank_mask:0xf
	v_fmac_f32_dpp v107, v103, v57 row_newbcast:9 row_mask:0xf bank_mask:0xf
	v_fmac_f32_dpp v104, v100, v10 row_newbcast:10 row_mask:0xf bank_mask:0xf
	v_fmac_f32_dpp v105, v101, v26 row_newbcast:10 row_mask:0xf bank_mask:0xf
	v_fmac_f32_dpp v106, v102, v42 row_newbcast:10 row_mask:0xf bank_mask:0xf
	v_fmac_f32_dpp v107, v103, v58 row_newbcast:10 row_mask:0xf bank_mask:0xf
	v_fmac_f32_dpp v104, v100, v11 row_newbcast:11 row_mask:0xf bank_mask:0xf
	v_fmac_f32_dpp v105, v101, v27 row_newbcast:11 row_mask:0xf bank_mask:0xf
	v_fmac_f32_dpp v106, v102, v43 row_newbcast:11 row_mask:0xf bank_mask:0xf
	v_fmac_f32_dpp v107, v103, v59 row_newbcast:11 row_mask:0xf bank_mask:0xf
	v_fmac_f32_dpp v104, v100, v12 row_newbcast:12 row_mask:0xf bank_mask:0xf
	v_fmac_f32_dpp v105, v101, v28 row_newbcast:12 row_mask:0xf bank_mask:0xf
	v_fmac_f32_dpp v106, v102, v44 row_newbcast:12 row_mask:0xf bank_mask:0xf
	v_fmac_f32_dpp v107, v103, v60 row_newbcast:12 row_mask:0xf bank_mask:0xf
	v_fmac_f32_dpp v104, v100, v13 row_newbcast:13 row_mask:0xf bank_mask:0xf
	v_fmac_f32_dpp v105, v101, v29 row_newbcast:13 row_mask:0xf bank_mask:0xf
	v_fmac_f32_dpp v106, v102, v45 row_newbcast:13 row_mask:0xf bank_mask:0xf
	v_fmac_f32_dpp v107, v103, v61 row_newbcast:13 row_mask:0xf bank_mask:0xf
	v_fmac_f32_dpp v104, v100, v14 row_newbcast:14 row_mask:0xf bank_mask:0xf
	v_fmac_f32_dpp v105, v101, v30 row_newbcast:14 row_mask:0xf bank_mask:0xf
	v_fmac_f32_dpp v106, v102, v46 row_newbcast:14 row_mask:0xf bank_mask:0xf
	v_fmac_f32_dpp v107, v103, v62 row_newbcast:14 row_mask:0xf bank_mask:0xf
	v_fmac_f32_dpp v104, v100, v15 row_newbcast:15 row_mask:0xf bank_mask:0xf
	v_fmac_f32_dpp v105, v101, v31 row_newbcast:15 row_mask:0xf bank_mask:0xf
	v_fmac_f32_dpp v106, v102, v47 row_newbcast:15 row_mask:0xf bank_mask:0xf
	v_fmac_f32_dpp v107, v103, v63 row_newbcast:15 row_mask:0xf bank_mask:0xf
	v_add_f32_e32 v104, v104, v105
	v_add_f32_e32 v106, v106, v107
	v_add_f32_e32 v104, v104, v106
	ds_write_b32 v110, v104
	s_add_u32 s6, s68, s73
	s_addc_u32 s7, s69, 0
	global_store_dword v113, v104, s[6:7]
	s_add_u32 s73, s73, 0x4000
	ds_read_b32 v100, v111 offset:0
	ds_read_b32 v101, v111 offset:64
	ds_read_b32 v102, v111 offset:128
	ds_read_b32 v103, v111 offset:192
	s_xor_b32 s74, s74, 0x4400
	v_add_u32_e32 v114, s74, v109
	ds_write_b128 v114, v[88:91]
	ds_write_b128 v114, v[92:95] offset:16
	s_min_u32 s4, s70, 0xf8000
	s_add_u32 s6, s64, s4
	s_addc_u32 s7, s65, 0
	s_nop 0
	global_load_dwordx4 v[88:91], v112, s[6:7]
	global_load_dwordx4 v[92:95], v112, s[6:7] offset:16
	s_min_u32 s4, s71, 0xf8000
	s_add_u32 s6, s66, s4
	s_addc_u32 s7, s67, 0
	global_load_dword v96, v113, s[6:7]
	s_add_u32 s70, s70, 0x4000
	s_add_u32 s71, s71, 0x4000
	s_waitcnt lgkmcnt(0)
	s_barrier
	s_sub_u32 s72, s72, 1
	s_cmp_lg_u32 s72, 0
	s_cbranch_scc1 .Lmy_cmb0_loop
	s_add_i32 s0, s0, s96
	s_branch .Lmy_cmb0_item

; #define NEXT_ITEM() (MIX ? (int)__builtin_amdgcn_readfirstlane(lane == 0 ? __hip_atomic_fetch_add(qctr, 1u, __ATOMIC_RELAXED, __HIP_MEMORY_SCOPE_AGENT) : 0u) : item + (int)gridDim.x * 8)
; template <bool MIX> __device__ __forceinline__ void scan_pass1(const Params& p, int d, float* ldsf) {
;     ...
;     for (int item = MIX ? NEXT_ITEM() : (int)(blockIdx.x * 8 + wid); item < 2 * NS; item = NEXT_ITEM()) {
.Lmy_p1d1_stored:
	s_nop 1
	s_lshl_b32 s6, s96, 3
	s_add_i32 s0, s0, s6
	s_branch .Lmy_p1d1_item

; #define LAS __attribute__((address_space(3)))
; __device__ __forceinline__ void scan_combine(const Params& p, unsigned char* lds) {
;     const int tid = threadIdx.x, lane = tid & 63, wid = __builtin_amdgcn_readfirstlane(tid >> 6), l15 = lane & 15;
;     const float* PT = (const float*)(p.ws + O_PT); const float* SLT = (const float*)(p.ws + O_SLT); float* SIT = (float*)(p.ws + O_SIT);
;     LAS float* pbuf = (LAS float*)(LAS unsigned char*)lds;
;     LAS float* rowb = pbuf + 8192 + wid * 64;
;     for (int item = blockIdx.x; item < 256; item += gridDim.x) {
;         const int bh = item >> 3, row = (item & 7) * 8 + wid;
;         const float* pt = PT + (size_t)bh * NC * 4096 + tid * 8; const float* st = SLT + (size_t)bh * NC * 4096 + row * 64 + lane; float* si = SIT + (size_t)bh * NC * 4096 + row * 64 + lane;
.LBB0_893:
	s_cmp_lt_i32 s58, 10
	s_cselect_b64 s[0:1], -1, 0
	s_cmp_gt_i32 s59, 9
	s_cselect_b64 s[4:5], -1, 0
	s_and_b64 s[0:1], s[0:1], s[4:5]
	s_andn2_b64 vcc, exec, s[0:1]
	s_cbranch_vccnz .LBB0_953
	v_readfirstlane_b32 s0, v254
	s_nop 3
	s_lshr_b32 s1, s0, 6
	v_and_b32_e32 v114, 63, v254
	v_lshlrev_b32_e32 v108, 2, v114
	v_mul_u32_u24_e32 v116, 272, v114
	v_lshlrev_b32_e32 v112, 5, v254
	v_lshrrev_b32_e32 v109, 3, v254
	v_mul_u32_u24_e32 v109, 272, v109
	v_and_b32_e32 v115, 7, v254
	v_lshl_add_u32 v109, v115, 5, v109
	s_lshl_b32 s4, s1, 8
	s_add_u32 s4, s4, 0x9000
	v_add_u32_e32 v110, s4, v108
	v_and_b32_e32 v115, 15, v254
	v_lshlrev_b32_e32 v115, 2, v115
	v_add_u32_e32 v111, s4, v115
	s_mov_b32 s0, s2
